# P8/P9: sample-row small GEMM before the main unit + per-(XCD,row-tile) arrival counters; the final grid barrier (seam 8) removed, P9 owners only check their row tile's 32 signals (on v48)
# speedup vs baseline: 1.0148x; 1.0148x over previous
;     __device__ __forceinline__ float* ctl() const { return (float*)(ws + WS_CTL); }
;     __device__ __forceinline__ bf16_t* W2_t() const { return (bf16_t*)(ws + WS_W2); }
;     __device__ __forceinline__ bf16_t* R2B() const { return (bf16_t*)(ws + WS_R2B); }
;     __device__ __forceinline__ bf16_t* H() const { return (bf16_t*)(ws + WS_H); }
;     __device__ __forceinline__ float* R1() const { return (float*)(ws + WS_R1); }
; #define GEMM_PHASE(EpiT, E, A_, B_, M_, N_, K_, c_) do { pg8::Gemm g_{A_, B_, M_, N_, K_}; pg8::StaticOrder S_; S_.init(M_, N_, G, c_); \
;         pg8::gemm_phase<EpiT, pg8::StaticOrder, true, true>(lds, g_, S_, E); } while (0)
; __global__ void __launch_bounds__(512, 2) fwd_megakernel(Args a) {
;     ...
;     const bool fused_ln3 = (G == 256);
;     if (IN(8)) {
;     ...
;             EpiLn3 E{p.R2B(), p.ctl() + CF_ST2, p.ln2_g(), p.ln2_b(), p.b2(), p.ln3_g(), p.ln3_b(), p.out() + OY, st};
;             pg8::Gemm g_{p.H(), p.W2_t(), NPT, DM, DFF}; pg8::StaticOrder S_; S_.init(NPT, DM, G, bid);
;             pg8::gemm_phase<EpiLn3, pg8::StaticOrder, false, true>(lds, g_, S_, E); }
;         else { typedef EpiRes<1, true, false, false, true> EpiT; EpiT E{p.R2B(), p.ctl() + CF_ST2, p.ln2_g(), p.ln2_b(), p.R1(), nullptr, nullptr, p.b2()};
;           GEMM_PHASE(EpiT, E, p.H(), p.W2_t(), NPT, DM, DFF, bid); }
;         { SmallRes<1, true, false, false, true> E{p.R2B(), p.ctl() + CF_ST2, p.ln2_g(), p.ln2_b(), p.R1(), nullptr, nullptr, p.b2()}; small_gemm_phase<32>(lds, p.H(), p.W2_t(), DFF, DFF, DM / 32, E, 0, G, bid, tid); }
.LBB0_1192:
	s_cmpk_eq_i32 s96, 0x100
	s_cselect_b64 s[6:7], -1, 0
	s_cmpk_lg_i32 s96, 0x100
	s_cselect_b64 s[0:1], -1, 0
	s_cmp_lt_i32 s88, 9
	s_cselect_b64 s[2:3], -1, 0
	s_cmp_gt_i32 s89, 8
	s_cselect_b64 s[4:5], -1, 0
	s_and_b64 s[2:3], s[2:3], s[4:5]
	s_andn2_b64 vcc, exec, s[2:3]
	s_cbranch_vccnz .LBB0_1350
	v_and_b32_e32 v196, 15, v192
	s_branch .Lp8_small
.Lp8_main:
	s_cmpk_lg_i32 s96, 0x100
	s_cselect_b64 s[0:1], -1, 0
	s_and_b64 vcc, exec, s[0:1]
	s_cbranch_vccz .LBB0_1197
	v_readfirstlane_b32 s3, v192
	s_cmpk_gt_i32 s94, 0xff
	v_and_b32_e32 v196, 15, v192
	s_cbranch_scc1 .LBB0_1219
	s_ashr_i32 s17, s94, 31
	s_lshr_b32 s0, s17, 29
	s_add_i32 s5, s94, s0
	s_and_b32 s0, s5, -8
	s_sub_i32 s4, s94, s0
	s_cmp_gt_i32 s4, -1
	s_cbranch_scc0 .LBB0_1198
	s_lshl_b32 s2, s4, 5
	s_ashr_i32 s0, s5, 3
	s_cbranch_execz .LBB0_1199
	s_branch .LBB0_1200

; #define LAS __attribute__((address_space(3)))
; __device__ __forceinline__ float bflo(unsigned v) { return __uint_as_float(v << 16); }
; template <int NC, class Epi>
; __device__ __forceinline__ void small_gemm_phase(LAS unsigned char* lds, const bf16_t* A, const bf16_t* Bt, int K, int ld, int ncolt  , const Epi& E, int first, int nblk, int bid, int tid) {
;     const int lane = tid & 63, wid = tid >> 6, fr = lane & 15, fq = lane >> 4, mt = wid >> 1, nh = wid & 1;
;     const int ub = bid - first; if (ub < 0 || ub >= nblk) return;
;     const int nch = K >> 8;
;     BAR_LDS();
;     for (int u = ub; u < 8 * ncolt; u += nblk) {
;         const int rt = u & 7, ct = u >> 3;
;         const int row0 = NPT + 64 * rt, col0 = NC * ct;
;         u32x4 ra[2][4], rb[2][4];
;     ...
;         SG_LOAD(0, 0); SG_LOAD(1, 1);
;         f32x4 acc0 = {0.f, 0.f, 0.f, 0.f}, acc1 = {0.f, 0.f, 0.f, 0.f};
;         const LAS unsigned char* apl = lds + (16 * mt + fr) * SG_STRIDE + 16 * fq;
;         const LAS unsigned char* bpl = lds + SG_BOFF + ((NC / 2) * nh + fr) * SG_STRIDE + 16 * fq;
; #pragma unroll 1
;         for (int kc = 0; kc < nch; kc += 2) { SG_STEP(kc, 0); SG_STEP(kc + 1, 1); }
;     __device__ __forceinline__ void operator()(int row, int colb, int fq, f32x4 acc0, f32x4 acc1, int nt) const {
;         float mu = 0.f, rs = 1.f;
;         if (MODE == 1) { const f32x2v s2 = *(const f32x2v*)(stp + 2 * row); mu = s2.x * (1.0f / DM); rs = rsqrtf(fmaxf(s2.y * (1.0f / DM) - mu * mu, 0.f) + LN_EPS); }
;         const bf16_t* xrow = xb + (size_t)row * DM;
;         float sum = 0.f, sq = 0.f;
; #pragma unroll
;         for (int t = 0; t < 2; ++t) { if (t >= nt) break; const int col = colb + 16 * t + 4 * fq;
;             const u32x2 xw = *(const u32x2*)(xrow + col); f32x4 xv = {bflo(xw.x), bfhi(xw.x), bflo(xw.y), bfhi(xw.y)};
;             if (MODE == 1) xv = (xv - mu) * rs * *(const f32x4*)(g + col) + *(const f32x4*)(b + col);
;             f32x4 r = xv * DN_ALPHA + (t ? acc1 : acc0);
;             if (HAS_BIAS) r = r + *(const f32x4*)(bias + col);
;             if (HAS_F32) *(f32x4*)(Rout + (size_t)row * DM + col) = r;
;             if (HAS_BF) { u32x2 w; w.x = pk2(r[0], r[1]); w.y = pk2(r[2], r[3]); *(u32x2*)(Rb + (size_t)row * DM + col) = w; }
;             if (HAS_STATS) { sum += (r[0] + r[1]) + (r[2] + r[3]); sq += (r[0] * r[0] + r[1] * r[1]) + (r[2] * r[2] + r[3] * r[3]); } }
.LBB0_1284:
	v_mov_b32_e32 v196, v193
.LBB0_1285:
	s_branch .Lp8_tail
.Lp8_small:
	s_cmp_lt_i32 s94, 0
	s_cselect_b64 s[0:1], -1, 0
	s_cmp_ge_i32 s94, s96
	s_cselect_b64 s[2:3], -1, 0
	s_or_b64 s[0:1], s[0:1], s[2:3]
	s_and_b64 vcc, exec, s[0:1]
	s_cbranch_vccnz .LBB0_1296
	s_waitcnt lgkmcnt(0)
	s_barrier
	s_cmpk_gt_u32 s94, 0xff
	s_cbranch_scc1 .LBB0_1295
	v_lshlrev_b32_e32 v0, 4, v192
	s_waitcnt vmcnt(0)
	v_and_b32_e32 v52, 0x1f0, v0
	v_mov_b32_e32 v53, 0
	s_waitcnt lgkmcnt(1)
	v_lshl_add_u64 v[0:1], s[58:59], 0, v[52:53]
	s_mov_b64 s[8:9], 0x2c00000
	v_lshl_add_u64 v[54:55], v[0:1], 0, s[8:9]
	s_mov_b64 s[8:9], 0x1700000
	v_lshl_add_u64 v[56:57], v[0:1], 0, s[8:9]
	v_lshrrev_b32_e32 v0, 3, v192
	s_movk_i32 s8, 0x70
	s_add_u32 s0, s58, 0x17600000
	v_bfe_u32 v2, v192, 4, 2
	v_and_or_b32 v86, v0, s8, v196
	s_addc_u32 s1, s59, 0
	v_mul_u32_u24_e32 v0, 0x210, v86
	v_lshlrev_b32_e32 v1, 4, v2
	s_add_u32 s2, s58, 0x22000
	v_add3_u32 v87, 0, v0, v1
	v_lshrrev_b32_e32 v0, 2, v192
	s_addc_u32 s3, s59, 0
	v_and_b32_e32 v0, 16, v0
	s_add_u32 s4, s58, 0xf200000
	s_waitcnt lgkmcnt(0)
	v_or_b32_e32 v3, v0, v196
	s_addc_u32 s5, s59, 0
	v_mul_u32_u24_e32 v3, 0x210, v3
	s_add_i32 s8, 0, 0x10800
	v_lshl_or_b32 v94, v2, 2, v0
	v_add_u32_e32 v0, 0x200, v192
	v_add3_u32 v88, 0, v3, v1
	v_add_u32_e32 v90, s8, v52
	s_add_i32 s8, 0, 0x18c00
	v_lshrrev_b32_e32 v96, 5, v0
	v_add_u32_e32 v1, 0x600, v192
	v_lshlrev_b32_e32 v0, 8, v0
	v_add_u32_e32 v89, 0, v52
	v_add_u32_e32 v91, s8, v52
	v_lshrrev_b32_e32 v95, 5, v192
	v_lshrrev_b32_e32 v98, 5, v1
	v_and_b32_e32 v1, 31, v192
	v_and_b32_e32 v52, 0x7e000, v0
	s_mov_b32 s9, 0
	v_add_u32_e32 v92, 0x10800, v87
	v_add_u32_e32 v93, 0x18c00, v88
	v_or_b32_e32 v97, 32, v95
	v_mul_u32_u24_e32 v99, 0x210, v95
	v_mul_u32_u24_e32 v100, 0x210, v96
	v_mul_u32_u24_e32 v101, 0x210, v98
	v_add_u32_e32 v102, 0x10840, v87
	v_add_u32_e32 v103, 0x18c40, v88
	v_add_u32_e32 v104, 0x10880, v87
	v_add_u32_e32 v105, 0x18c80, v88
	v_add_u32_e32 v106, 0x108c0, v87
	v_add_u32_e32 v107, 0x18cc0, v88
	v_add_u32_e32 v108, 0x10900, v87
	v_add_u32_e32 v109, 0x18d00, v88
	v_add_u32_e32 v110, 0x10940, v87
	v_add_u32_e32 v111, 0x18d40, v88
	v_add_u32_e32 v112, 0x10980, v87
	v_add_u32_e32 v113, 0x18d80, v88
	v_add_u32_e32 v114, 0x109c0, v87
	v_add_u32_e32 v115, 0x18dc0, v88
	v_lshlrev_b32_e32 v58, 4, v1
	v_mov_b32_e32 v59, v53
	v_lshl_add_u64 v[60:61], s[58:59], 0, v[52:53]
	s_lshl_b32 s13, s94, 2
	s_lshl_b32 s15, s96, 2
	v_or_b32_e32 v116, 0x4000, v98
	s_lshl_b32 s18, s94, 6
	s_lshl_b32 s19, s96, 6
	v_or_b32_e32 v117, 0x4020, v95
	v_or_b32_e32 v118, 0x4000, v96
	v_or_b32_e32 v119, 0x4000, v95
	s_mov_b64 s[10:11], 0x400
	s_mov_b32 s12, 0x3a800000
	s_mov_b32 s20, 0x800000
	s_mov_b32 s14, 0x3f9837f0
	s_mov_b32 s21, s94
	s_branch .LBB0_1289
.LBB0_1288:
	v_add_u32_e32 v18, s23, v86
	v_lshlrev_b32_e32 v52, 1, v18
	v_lshl_add_u64 v[0:1], v[52:53], 2, s[2:3]
	global_load_dwordx2 v[12:13], v[0:1], off
	v_lshlrev_b32_e32 v0, 11, v18
	v_mov_b32_e32 v1, v53
	v_or_b32_e32 v2, s22, v94
	v_lshl_add_u64 v[0:1], s[0:1], 0, v[0:1]
	s_waitcnt vmcnt(6)
	v_lshlrev_b32_e32 v4, 1, v2
	v_mov_b32_e32 v5, v53
	v_lshl_add_u64 v[0:1], v[0:1], 0, v[4:5]
	global_load_dwordx2 v[14:15], v[0:1], off
	v_readlane_b32 s60, v242, 3
	v_mov_b32_e32 v3, v53
	v_readlane_b32 s72, v242, 15
	v_readlane_b32 s73, v242, 16
	v_lshlrev_b64 v[16:17], 2, v[2:3]
	v_readlane_b32 s74, v242, 17
	v_readlane_b32 s75, v242, 18
	s_mov_b64 s[24:25], s[72:73]
	s_mov_b64 s[26:27], s[74:75]
	v_lshl_add_u64 v[8:9], s[24:25], 0, v[16:17]
	v_lshl_add_u64 v[10:11], s[26:27], 0, v[16:17]
	global_load_dwordx4 v[0:3], v[8:9], off
	global_load_dwordx4 v[4:7], v[10:11], off
	v_lshl_add_u64 v[8:9], s[50:51], 0, v[16:17]
	global_load_dwordx4 v[8:11], v[8:9], off
	s_add_i32 s13, s13, s15
	v_lshlrev_b32_e32 v52, 10, v18
	v_lshl_add_u64 v[18:19], v[52:53], 2, s[4:5]
	v_lshl_add_u64 v[16:17], v[18:19], 0, v[16:17]
	s_add_i32 s21, s21, s96
	s_add_i32 s18, s18, s19
	s_cmpk_gt_i32 s21, 0xff
	v_readlane_b32 s61, v242, 4
	v_readlane_b32 s62, v242, 5
	v_readlane_b32 s63, v242, 6
	v_readlane_b32 s64, v242, 7
	v_readlane_b32 s65, v242, 8
	v_readlane_b32 s66, v242, 9
	v_readlane_b32 s67, v242, 10
	v_readlane_b32 s68, v242, 11
	v_readlane_b32 s69, v242, 12
	v_readlane_b32 s70, v242, 13
	v_readlane_b32 s71, v242, 14
	s_waitcnt vmcnt(4)
	v_pk_mul_f32 v[12:13], v[12:13], s[12:13] op_sel_hi:[1,0]
	s_nop 0
	v_fma_f32 v13, -v12, v12, v13
	v_max_f32_e32 v13, 0, v13
	v_add_f32_e32 v13, 0x3727c5ac, v13
	v_mul_f32_e32 v20, 0x4b800000, v13
	v_cmp_gt_f32_e32 vcc, s20, v13
	s_waitcnt vmcnt(3)
	v_lshlrev_b32_e32 v18, 16, v14
	v_cndmask_b32_e32 v13, v13, v20, vcc
	v_rsq_f32_e32 v20, v13
	v_and_b32_e32 v19, 0xffff0000, v14
	v_lshlrev_b32_e32 v14, 16, v15
	v_and_b32_e32 v15, 0xffff0000, v15
	v_sub_f32_e32 v15, v15, v12
	v_sub_f32_e32 v14, v14, v12
	v_sub_f32_e32 v13, v19, v12
	v_sub_f32_e32 v12, v18, v12
	v_mul_f32_e32 v18, 0x45800000, v20
	v_cndmask_b32_e32 v18, v20, v18, vcc
	v_pk_mul_f32 v[12:13], v[12:13], v[18:19] op_sel_hi:[1,0]
	v_pk_mul_f32 v[14:15], v[14:15], v[18:19] op_sel_hi:[1,0]
	s_waitcnt vmcnt(1)
	v_pk_fma_f32 v[0:1], v[0:1], v[12:13], v[4:5]
	v_pk_fma_f32 v[2:3], v[2:3], v[14:15], v[6:7]
	v_pk_fma_f32 v[0:1], v[0:1], s[14:15], v[48:49] op_sel_hi:[1,0,1]
	v_pk_fma_f32 v[2:3], v[2:3], s[14:15], v[50:51] op_sel_hi:[1,0,1]
	s_waitcnt vmcnt(0)
	v_pk_add_f32 v[0:1], v[8:9], v[0:1]
	v_pk_add_f32 v[2:3], v[10:11], v[2:3]
	global_store_dwordx4 v[16:17], v[0:3], off sc1
	s_cbranch_scc1 .LBB0_1295

;     __device__ __forceinline__ float* ctl() const { return (float*)(ws + WS_CTL); }
;     __device__ __forceinline__ bf16_t* W2_t() const { return (bf16_t*)(ws + WS_W2); }
;     __device__ __forceinline__ bf16_t* R2B() const { return (bf16_t*)(ws + WS_R2B); }
;     __device__ __forceinline__ bf16_t* H() const { return (bf16_t*)(ws + WS_H); }
;     __device__ __forceinline__ float* R1() const { return (float*)(ws + WS_R1); }
; __device__ __forceinline__ unsigned xb_ld(unsigned* p)              { return __hip_atomic_load(p, __ATOMIC_RELAXED, __HIP_MEMORY_SCOPE_AGENT); }
; #define SEAM(k) do { if ((k) + 1 < hi) xcd_barrier(bar); } while (0)
; __device__ __forceinline__ void xcd_barrier(const XcdBarrier& b) {
;     asm volatile("s_waitcnt vmcnt(0)" ::: "memory");
;     __syncthreads();
;     if (threadIdx.x == 0) {
;         unsigned* bar = b.bar;
;         __builtin_amdgcn_s_waitcnt(0);
;         unsigned nloc = b.st[0], nx = b.st[1];
;         if (nloc == 0u) { xcd_barrier_complete(bar, b.x, nloc, nx); b.st[0] = nloc; b.st[1] = nx; }
;         const unsigned old = xb_add(&bar[XB_XSUB(b.x)], 1u);
;         const unsigned gen = old / nloc;
;         if (old + 1u == (gen + 1u) * nloc) {
;             __builtin_amdgcn_fence(__ATOMIC_RELEASE, "agent");
;             asm volatile("s_waitcnt vmcnt(0)" ::: "memory");
;             const unsigned og = xb_add(&bar[XB_TOP], 1u);
;             const unsigned tg = og / nx;
;             if (og + 1u == (tg + 1u) * nx) xb_add(&bar[XB_TOPGEN], 1u);
;             else XB_SPIN(xb_ld(&bar[XB_TOPGEN]) == tg, bar);
;             __builtin_amdgcn_fence(__ATOMIC_ACQUIRE, "agent");
;             xb_add(&bar[XB_XGEN(b.x)], 1u);
;             asm volatile("s_waitcnt vmcnt(0)" ::: "memory");
;         } else {
;             XB_SPIN(xb_ld(&bar[XB_XGEN(b.x)]) == gen, bar);
;             __builtin_amdgcn_fence(__ATOMIC_ACQUIRE, "agent");
;             asm volatile("s_waitcnt vmcnt(0)" ::: "memory");
;         }
;     }
;     __syncthreads();
; }
; __global__ void __launch_bounds__(512, 2) fwd_megakernel(Args a) {
;     ...
;         { SmallRes<1, true, false, false, true> E{p.R2B(), p.ctl() + CF_ST2, p.ln2_g(), p.ln2_b(), p.R1(), nullptr, nullptr, p.b2()}; small_gemm_phase<32>(lds, p.H(), p.W2_t(), DFF, DFF, DM / 32, E, 0, G, bid, tid); }
;         SEAM(8); }
;     if (IN(9)) { p9_ln3(p, G, bid, tid, fused_ln3 ? NPT : 0); }
.LBB0_1296:
	s_waitcnt vmcnt(0)
	s_barrier
	v_cmp_eq_u32_e32 vcc, 0, v192
	s_and_saveexec_b64 s[0:1], vcc
	s_cbranch_execz .Lp8_arrived
	s_lshl_b32 s2, s84, 3
	s_and_b32 s3, s94, 7
	s_add_u32 s2, s2, s3
	s_lshl_b32 s2, s2, 2
	v_mov_b32_e32 v0, s2
	v_mov_b32_e32 v1, 1
	s_add_u32 s4, s58, 0x60000
	s_addc_u32 s5, s59, 0
	global_atomic_add v0, v1, s[4:5]
.Lp8_arrived:
	s_or_b64 exec, exec, s[0:1]
	s_branch .Lp8_main
.Lp8_tail:
	s_cmp_gt_u32 s94, 63
	s_cbranch_scc1 .LBB0_1350
	v_and_b32_e32 v0, 63, v192
	s_lshr_b32 s2, s94, 3
	v_lshl_add_u32 v2, v0, 3, s2
	v_lshlrev_b32_e32 v2, 2, v2
	s_add_u32 s4, s58, 0x60000
	s_addc_u32 s5, s59, 0
	s_mov_b64 s[0:1], exec
	v_cmp_gt_u32_e32 vcc, 16, v0
	s_and_b64 exec, exec, vcc
.Lp8_poll:
	global_load_dword v1, v2, s[4:5] sc1
	s_waitcnt vmcnt(0)
	s_mov_b32 s3, 0
	v_readlane_b32 s2, v1, 0
	s_nop 0
	s_add_u32 s3, s3, s2
	v_readlane_b32 s2, v1, 1
	s_nop 0
	s_add_u32 s3, s3, s2
	v_readlane_b32 s2, v1, 2
	s_nop 0
	s_add_u32 s3, s3, s2
	v_readlane_b32 s2, v1, 3
	s_nop 0
	s_add_u32 s3, s3, s2
	v_readlane_b32 s2, v1, 4
	s_nop 0
	s_add_u32 s3, s3, s2
	v_readlane_b32 s2, v1, 5
	s_nop 0
	s_add_u32 s3, s3, s2
	v_readlane_b32 s2, v1, 6
	s_nop 0
	s_add_u32 s3, s3, s2
	v_readlane_b32 s2, v1, 7
	s_nop 0
	s_add_u32 s3, s3, s2
	v_readlane_b32 s2, v1, 8
	s_nop 0
	s_add_u32 s3, s3, s2
	v_readlane_b32 s2, v1, 9
	s_nop 0
	s_add_u32 s3, s3, s2
	v_readlane_b32 s2, v1, 10
	s_nop 0
	s_add_u32 s3, s3, s2
	v_readlane_b32 s2, v1, 11
	s_nop 0
	s_add_u32 s3, s3, s2
	v_readlane_b32 s2, v1, 12
	s_nop 0
	s_add_u32 s3, s3, s2
	v_readlane_b32 s2, v1, 13
	s_nop 0
	s_add_u32 s3, s3, s2
	v_readlane_b32 s2, v1, 14
	s_nop 0
	s_add_u32 s3, s3, s2
	v_readlane_b32 s2, v1, 15
	s_nop 0
	s_add_u32 s3, s3, s2
	s_cmp_ge_u32 s3, 32
	s_cbranch_scc1 .Lp8_ready
	s_sleep 1
	s_branch .Lp8_poll
.Lp8_ready:
	s_mov_b64 exec, s[0:1]
	buffer_inv sc1
